# v73 + rw_post stage 1: counted vmcnt ladder between the 16 operand loads and their LDS writes (both blocks)
# speedup vs baseline: 1.0021x; 1.0001x over previous
; __device__ __forceinline__ void rw_post(Frame& F) {
;     ...
;     for (int u = F.gw; u < 32 * (MR / 64); u += F.NGW) { const int h = u & 31, rb0 = (u >> 5) * 64, col = h * 64 + lane;
;         const float g_ = lng[col], b_ = lnb[col];
;         const int k = rb0 < MPR ? (rb0 / SEGLEN) : 0;
;         f32x4 Sr[16];
;         if (k > 0) {
; #pragma unroll
;             for (int q = 0; q < 16; ++q) Sr[q] = *(const f32x4*)(SST + ((size_t)(h * NSEG + k) * 64 + lane) * 64 + 4 * q); }
;         const float* yp = Y + (size_t)rb0 * DH + col; const float* vp = VS + (size_t)rb0 * DH + col; const bf16* gp = G + (size_t)rb0 * DH + col; const float* rp = RK + (size_t)rb0 * 32 + h;
;         const float* cp = k > 0 ? C + (size_t)(rb0 - SEGLEN) * DH + col : yp;
.Lpo_unit:
	s_and_b32 s21, s20, 31
	s_lshr_b32 s22, s20, 5
	s_lshl_b32 s22, s22, 6
	s_lshr_b32 s23, s22, 10
	s_cmpk_lt_i32 s22, 0x4000
	s_cselect_b32 s23, s23, 0
	s_add_i32 s34, s22, s33
	s_and_b32 s35, s21, 24
	s_lshl_b32 s30, s34, 13
	s_lshl_b32 s31, s35, 8
	s_add_u32 s30, s30, s31
	s_add_u32 s6, s90, s30
	s_addc_u32 s7, s91, 0
	s_add_u32 s8, s6, 0x28700000
	s_addc_u32 s9, s7, 0
	s_add_u32 s6, s6, 0x39900000
	s_addc_u32 s7, s7, 0
	s_lshl_b32 s30, s34, 12
	s_lshl_b32 s31, s35, 7
	s_add_u32 s30, s30, s31
	s_add_u32 s10, s90, s30
	s_addc_u32 s11, s91, 0
	s_add_u32 s10, s10, 0x30800000
	s_addc_u32 s11, s11, 0
	s_lshl_b32 s30, s22, 12
	s_lshl_b32 s31, s21, 7
	s_add_u32 s30, s30, s31
	s_add_u32 s28, s90, s30
	s_addc_u32 s29, s91, 0
	s_add_u32 s28, s28, 0x18500000
	s_addc_u32 s29, s29, 0
	s_lshl_b32 s30, s22, 7
	s_lshl_b32 s31, s21, 2
	s_add_u32 s30, s30, s31
	s_add_u32 s12, s90, s30
	s_addc_u32 s13, s91, 0
	s_add_u32 s12, s12, 0x6e200000
	s_addc_u32 s13, s13, 0
	s_lshl_b32 s31, s21, 8
	s_add_u32 s30, s16, s31
	s_addc_u32 s31, s17, 0
	global_load_dword v6, v1, s[30:31]
	s_lshl_b32 s31, s21, 8
	s_add_u32 s30, s18, s31
	s_addc_u32 s31, s19, 0
	global_load_dword v7, v1, s[30:31]
	s_barrier
	s_cmp_eq_u32 s23, 0
	s_cbranch_scc1 .Lpo_zero
	s_lshl_b32 s30, s21, 4
	s_add_u32 s30, s30, s23
	s_lshl_b32 s30, s30, 14
	s_add_u32 s30, s90, s30
	s_addc_u32 s31, s91, 0
	s_add_u32 s30, s30, 0x6fb00000
	s_addc_u32 s31, s31, 0
	s_lshl_b32 s34, s22, 13
	s_lshl_b32 s35, s21, 8
	s_add_u32 s34, s34, s35
	s_add_u32 s34, s90, s34
	s_addc_u32 s35, s91, 0
	s_add_u32 s34, s34, 0x41200000
	s_addc_u32 s35, s35, 0
	v_lshrrev_b32_e32 v170, 4, v178
	v_and_b32_e32 v168, 15, v178
	v_lshlrev_b32_e32 v171, 4, v168
	v_lshl_add_u32 v171, v170, 13, v171
	v_mul_u32_u24_e32 v172, 0x110, v170
	v_lshl_add_u32 v172, v168, 3, v172
	s_mul_i32 s36, s33, 0x4400
	v_add_u32_e32 v172, s36, v172
	v_and_b32_e32 v170, 31, v178
	v_mul_u32_u24_e32 v173, 0x110, v170
	v_lshrrev_b32_e32 v168, 5, v178
	v_lshl_add_u32 v173, v168, 7, v173
	v_add_u32_e32 v173, s36, v173
	global_load_dwordx4 v[80:83], v11, s[30:31]
	global_load_dwordx4 v[84:87], v11, s[30:31] offset:1024
	global_load_dwordx4 v[88:91], v11, s[30:31] offset:2048
	global_load_dwordx4 v[92:95], v11, s[30:31] offset:3072
	s_add_u32 s30, s30, 0x1000
	s_addc_u32 s31, s31, 0
	global_load_dwordx4 v[96:99], v11, s[30:31]
	global_load_dwordx4 v[100:103], v11, s[30:31] offset:1024
	global_load_dwordx4 v[104:107], v11, s[30:31] offset:2048
	global_load_dwordx4 v[108:111], v11, s[30:31] offset:3072
	s_add_u32 s30, s30, 0x1000
	s_addc_u32 s31, s31, 0
	global_load_dwordx4 v[112:115], v11, s[30:31]
	global_load_dwordx4 v[116:119], v11, s[30:31] offset:1024
	global_load_dwordx4 v[120:123], v11, s[30:31] offset:2048
	global_load_dwordx4 v[124:127], v11, s[30:31] offset:3072
	s_add_u32 s30, s30, 0x1000
	s_addc_u32 s31, s31, 0
	global_load_dwordx4 v[128:131], v11, s[30:31]
	global_load_dwordx4 v[132:135], v11, s[30:31] offset:1024
	global_load_dwordx4 v[136:139], v11, s[30:31] offset:2048
	global_load_dwordx4 v[140:143], v11, s[30:31] offset:3072
	s_waitcnt vmcnt(15)
	ds_write_b32 v172, v80 offset:0
	ds_write_b32 v172, v82 offset:4
	ds_write_b32 v172, v81 offset:128
	ds_write_b32 v172, v83 offset:132
	s_waitcnt vmcnt(14)
	ds_write_b32 v172, v84 offset:1088
	ds_write_b32 v172, v86 offset:1092
	ds_write_b32 v172, v85 offset:1216
	ds_write_b32 v172, v87 offset:1220
	s_waitcnt vmcnt(13)
	ds_write_b32 v172, v88 offset:2176
	ds_write_b32 v172, v90 offset:2180
	ds_write_b32 v172, v89 offset:2304
	ds_write_b32 v172, v91 offset:2308
	s_waitcnt vmcnt(12)
	ds_write_b32 v172, v92 offset:3264
	ds_write_b32 v172, v94 offset:3268
	ds_write_b32 v172, v93 offset:3392
	ds_write_b32 v172, v95 offset:3396
	s_waitcnt vmcnt(11)
	ds_write_b32 v172, v96 offset:4352
	ds_write_b32 v172, v98 offset:4356
	ds_write_b32 v172, v97 offset:4480
	ds_write_b32 v172, v99 offset:4484
	s_waitcnt vmcnt(10)
	ds_write_b32 v172, v100 offset:5440
	ds_write_b32 v172, v102 offset:5444
	ds_write_b32 v172, v101 offset:5568
	ds_write_b32 v172, v103 offset:5572
	s_waitcnt vmcnt(9)
	ds_write_b32 v172, v104 offset:6528
	ds_write_b32 v172, v106 offset:6532
	ds_write_b32 v172, v105 offset:6656
	ds_write_b32 v172, v107 offset:6660
	s_waitcnt vmcnt(8)
	ds_write_b32 v172, v108 offset:7616
	ds_write_b32 v172, v110 offset:7620
	ds_write_b32 v172, v109 offset:7744
	ds_write_b32 v172, v111 offset:7748
	s_waitcnt vmcnt(7)
	ds_write_b32 v172, v112 offset:8704
	ds_write_b32 v172, v114 offset:8708
	ds_write_b32 v172, v113 offset:8832
	ds_write_b32 v172, v115 offset:8836
	s_waitcnt vmcnt(6)
	ds_write_b32 v172, v116 offset:9792
	ds_write_b32 v172, v118 offset:9796
	ds_write_b32 v172, v117 offset:9920
	ds_write_b32 v172, v119 offset:9924
	s_waitcnt vmcnt(5)
	ds_write_b32 v172, v120 offset:10880
	ds_write_b32 v172, v122 offset:10884
	ds_write_b32 v172, v121 offset:11008
	ds_write_b32 v172, v123 offset:11012
	s_waitcnt vmcnt(4)
	ds_write_b32 v172, v124 offset:11968
	ds_write_b32 v172, v126 offset:11972
	ds_write_b32 v172, v125 offset:12096
	ds_write_b32 v172, v127 offset:12100
	s_waitcnt vmcnt(3)
	ds_write_b32 v172, v128 offset:13056
	ds_write_b32 v172, v130 offset:13060
	ds_write_b32 v172, v129 offset:13184
	ds_write_b32 v172, v131 offset:13188
	s_waitcnt vmcnt(2)
	ds_write_b32 v172, v132 offset:14144
	ds_write_b32 v172, v134 offset:14148
	ds_write_b32 v172, v133 offset:14272
	ds_write_b32 v172, v135 offset:14276
	s_waitcnt vmcnt(1)
	ds_write_b32 v172, v136 offset:15232
	ds_write_b32 v172, v138 offset:15236
	ds_write_b32 v172, v137 offset:15360
	ds_write_b32 v172, v139 offset:15364
	s_waitcnt vmcnt(0)
; #define LAS __attribute__((address_space(3)))
; #define POST_LD(Y_, V_, G_, R_, C_, t) do { _Pragma("unroll") for (int q = 0; q < 8; ++q) { const size_t o_ = (size_t)((t) + q) * DH; Y_[q] = yp[o_]; V_[q] = vp[o_]; G_[q] = gp[o_]; R_[q] = rp[((t) + q) * 32]; C_[q] = cp[o_]; } } while (0)
; __device__ __forceinline__ void rw_post(Frame& F) {
;     ...
;         if (k > 0) {
; #pragma unroll
;             for (int q = 0; q < 16; ++q) Sr[q] = *(const f32x4*)(SST + ((size_t)(h * NSEG + k) * 64 + lane) * 64 + 4 * q); }
;         const float* yp = Y + (size_t)rb0 * DH + col; const float* vp = VS + (size_t)rb0 * DH + col; const bf16* gp = G + (size_t)rb0 * DH + col; const float* rp = RK + (size_t)rb0 * 32 + h;
;         const float* cp = k > 0 ? C + (size_t)(rb0 - SEGLEN) * DH + col : yp;
;         float y[8], vv[8], rk[8], cc[8]; bf16 gg[8];
;     ...
;         POST_LD(y, vv, gg, rk, cc, 0);
;         for (int t0 = 0; t0 < 64; t0 += 8) {
;             float ny[8], nv[8], nr[8], nc[8]; bf16 ng[8];
;             const int tn = t0 + 8 < 64 ? t0 + 8 : t0;
;             POST_LD(ny, nv, ng, nr, nc, tn);
;             if (k > 0) {
;                 LAS float* cs = (LAS float*)(F.lds + 131072 + F.wave * 1024);
; #pragma unroll
;                 for (int hf = 0; hf < 2; ++hf) {
; #pragma unroll
;                     for (int q = 0; q < 4; ++q) cs[q * 64 + lane] = cc[4 * hf + q];
;                     asm volatile("s_waitcnt lgkmcnt(0)" ::: "memory");
; #pragma unroll
;                     for (int q = 0; q < 4; ++q) { f32x4 a = (f32x4){0.f, 0.f, 0.f, 0.f};
; #pragma unroll
;                         for (int i = 0; i < 16; ++i) a = __builtin_elementwise_fma(Sr[i], *(const LAS f32x4*)(cs + q * 64 + 4 * i), a);
	ds_write_b32 v172, v140 offset:16320
	ds_write_b32 v172, v142 offset:16324
	ds_write_b32 v172, v141 offset:16448
	ds_write_b32 v172, v143 offset:16452
	s_waitcnt lgkmcnt(0)
	ds_read_b128 v[184:187], v173 offset:0
	ds_read_b128 v[188:191], v173 offset:16
	ds_read_b128 v[192:195], v173 offset:32
	ds_read_b128 v[196:199], v173 offset:48
	ds_read_b128 v[200:203], v173 offset:64
	ds_read_b128 v[204:207], v173 offset:80
	ds_read_b128 v[208:211], v173 offset:96
	ds_read_b128 v[212:215], v173 offset:112
	ds_read_b128 v[216:219], v173 offset:8704
	ds_read_b128 v[220:223], v173 offset:8720
	ds_read_b128 v[224:227], v173 offset:8736
	ds_read_b128 v[228:231], v173 offset:8752
	ds_read_b128 v[232:235], v173 offset:8768
	ds_read_b128 v[244:247], v173 offset:8784
	ds_read_b128 v[248:251], v173 offset:8800
	ds_read_b128 v[252:255], v173 offset:8816
	s_waitcnt lgkmcnt(0)
	global_load_dwordx4 v[80:83], v171, s[34:35]
	s_add_u32 s34, s34, 0x8000
	s_addc_u32 s35, s35, 0
	global_load_dwordx4 v[84:87], v171, s[34:35]
	s_add_u32 s34, s34, 0x8000
	s_addc_u32 s35, s35, 0
	global_load_dwordx4 v[88:91], v171, s[34:35]
	s_add_u32 s34, s34, 0x8000
	s_addc_u32 s35, s35, 0
	global_load_dwordx4 v[92:95], v171, s[34:35]
	s_add_u32 s34, s34, 0x8000
	s_addc_u32 s35, s35, 0
	global_load_dwordx4 v[96:99], v171, s[34:35]
	s_add_u32 s34, s34, 0x8000
	s_addc_u32 s35, s35, 0
	global_load_dwordx4 v[100:103], v171, s[34:35]
	s_add_u32 s34, s34, 0x8000
	s_addc_u32 s35, s35, 0
	global_load_dwordx4 v[104:107], v171, s[34:35]
	s_add_u32 s34, s34, 0x8000
	s_addc_u32 s35, s35, 0
	global_load_dwordx4 v[108:111], v171, s[34:35]
	s_add_u32 s34, s34, 0x8000
	s_addc_u32 s35, s35, 0
	global_load_dwordx4 v[112:115], v171, s[34:35]
	s_add_u32 s34, s34, 0x8000
	s_addc_u32 s35, s35, 0
	global_load_dwordx4 v[116:119], v171, s[34:35]
	s_add_u32 s34, s34, 0x8000
	s_addc_u32 s35, s35, 0
	global_load_dwordx4 v[120:123], v171, s[34:35]
	s_add_u32 s34, s34, 0x8000
	s_addc_u32 s35, s35, 0
	global_load_dwordx4 v[124:127], v171, s[34:35]
	s_add_u32 s34, s34, 0x8000
	s_addc_u32 s35, s35, 0
	global_load_dwordx4 v[128:131], v171, s[34:35]
	s_add_u32 s34, s34, 0x8000
	s_addc_u32 s35, s35, 0
	global_load_dwordx4 v[132:135], v171, s[34:35]
	s_add_u32 s34, s34, 0x8000
	s_addc_u32 s35, s35, 0
	global_load_dwordx4 v[136:139], v171, s[34:35]
	s_add_u32 s34, s34, 0x8000
	s_addc_u32 s35, s35, 0
	global_load_dwordx4 v[140:143], v171, s[34:35]
	s_waitcnt vmcnt(15)
	ds_write_b32 v172, v80 offset:0
	ds_write_b32 v172, v82 offset:4
	ds_write_b32 v172, v81 offset:128
	ds_write_b32 v172, v83 offset:132
	s_waitcnt vmcnt(14)
	ds_write_b32 v172, v84 offset:1088
	ds_write_b32 v172, v86 offset:1092
	ds_write_b32 v172, v85 offset:1216
	ds_write_b32 v172, v87 offset:1220
	s_waitcnt vmcnt(13)
	ds_write_b32 v172, v88 offset:2176
	ds_write_b32 v172, v90 offset:2180
	ds_write_b32 v172, v89 offset:2304
	ds_write_b32 v172, v91 offset:2308
	s_waitcnt vmcnt(12)
	ds_write_b32 v172, v92 offset:3264
	ds_write_b32 v172, v94 offset:3268
	ds_write_b32 v172, v93 offset:3392
	ds_write_b32 v172, v95 offset:3396
	s_waitcnt vmcnt(11)
	ds_write_b32 v172, v96 offset:4352
	ds_write_b32 v172, v98 offset:4356
	ds_write_b32 v172, v97 offset:4480
	ds_write_b32 v172, v99 offset:4484
	s_waitcnt vmcnt(10)
	ds_write_b32 v172, v100 offset:5440
	ds_write_b32 v172, v102 offset:5444
	ds_write_b32 v172, v101 offset:5568
	ds_write_b32 v172, v103 offset:5572
	s_waitcnt vmcnt(9)
	ds_write_b32 v172, v104 offset:6528
	ds_write_b32 v172, v106 offset:6532
	ds_write_b32 v172, v105 offset:6656
	ds_write_b32 v172, v107 offset:6660
	s_waitcnt vmcnt(8)
	ds_write_b32 v172, v108 offset:7616
	ds_write_b32 v172, v110 offset:7620
	ds_write_b32 v172, v109 offset:7744
	ds_write_b32 v172, v111 offset:7748
	s_waitcnt vmcnt(7)
	ds_write_b32 v172, v112 offset:8704
	ds_write_b32 v172, v114 offset:8708
	ds_write_b32 v172, v113 offset:8832
	ds_write_b32 v172, v115 offset:8836
	s_waitcnt vmcnt(6)
	ds_write_b32 v172, v116 offset:9792
	ds_write_b32 v172, v118 offset:9796
	ds_write_b32 v172, v117 offset:9920
	ds_write_b32 v172, v119 offset:9924
	s_waitcnt vmcnt(5)
	ds_write_b32 v172, v120 offset:10880
	ds_write_b32 v172, v122 offset:10884
	ds_write_b32 v172, v121 offset:11008
	ds_write_b32 v172, v123 offset:11012
	s_waitcnt vmcnt(4)
	ds_write_b32 v172, v124 offset:11968
	ds_write_b32 v172, v126 offset:11972
	ds_write_b32 v172, v125 offset:12096
	ds_write_b32 v172, v127 offset:12100
	s_waitcnt vmcnt(3)
	ds_write_b32 v172, v128 offset:13056
	ds_write_b32 v172, v130 offset:13060
	ds_write_b32 v172, v129 offset:13184
	ds_write_b32 v172, v131 offset:13188
	s_waitcnt vmcnt(2)
	ds_write_b32 v172, v132 offset:14144
	ds_write_b32 v172, v134 offset:14148
	ds_write_b32 v172, v133 offset:14272
	ds_write_b32 v172, v135 offset:14276
	s_waitcnt vmcnt(1)
	ds_write_b32 v172, v136 offset:15232
	ds_write_b32 v172, v138 offset:15236
	ds_write_b32 v172, v137 offset:15360
	ds_write_b32 v172, v139 offset:15364
	s_waitcnt vmcnt(0)
	ds_write_b32 v172, v140 offset:16320
	ds_write_b32 v172, v142 offset:16324
	ds_write_b32 v172, v141 offset:16448
	ds_write_b32 v172, v143 offset:16452
	s_waitcnt lgkmcnt(0)
	ds_read_b128 v[80:83], v173 offset:0
	ds_read_b128 v[84:87], v173 offset:16
	ds_read_b128 v[88:91], v173 offset:32
	ds_read_b128 v[92:95], v173 offset:48
	ds_read_b128 v[96:99], v173 offset:64
	ds_read_b128 v[100:103], v173 offset:80
	ds_read_b128 v[104:107], v173 offset:96
	ds_read_b128 v[108:111], v173 offset:112
	ds_read_b128 v[112:115], v173 offset:8704
	ds_read_b128 v[116:119], v173 offset:8720
	ds_read_b128 v[120:123], v173 offset:8736
	ds_read_b128 v[124:127], v173 offset:8752
	ds_read_b128 v[128:131], v173 offset:8768
	ds_read_b128 v[132:135], v173 offset:8784
	ds_read_b128 v[136:139], v173 offset:8800
	ds_read_b128 v[140:143], v173 offset:8816
	s_waitcnt lgkmcnt(0)
; #define LAS __attribute__((address_space(3)))
; __device__ __forceinline__ void rw_post(Frame& F) {
;     ...
;                     for (int q = 0; q < 4; ++q) { f32x4 a = (f32x4){0.f, 0.f, 0.f, 0.f};
; #pragma unroll
;                         for (int i = 0; i < 16; ++i) a = __builtin_elementwise_fma(Sr[i], *(const LAS f32x4*)(cs + q * 64 + 4 * i), a);
;                         y[4 * hf + q] += (a[0] + a[1]) + (a[2] + a[3]); }
	v_mfma_f32_32x32x2_f32 v[16:31], v80, v184, 0
	v_mfma_f32_32x32x2_f32 v[32:47], v80, v216, 0
	v_mfma_f32_32x32x2_f32 v[48:63], v112, v184, 0
	v_mfma_f32_32x32x2_f32 v[64:79], v112, v216, 0
	v_mfma_f32_32x32x2_f32 v[16:31], v81, v185, v[16:31]
	v_mfma_f32_32x32x2_f32 v[32:47], v81, v217, v[32:47]
	v_mfma_f32_32x32x2_f32 v[48:63], v113, v185, v[48:63]
	v_mfma_f32_32x32x2_f32 v[64:79], v113, v217, v[64:79]
	v_mfma_f32_32x32x2_f32 v[16:31], v82, v186, v[16:31]
	v_mfma_f32_32x32x2_f32 v[32:47], v82, v218, v[32:47]
	v_mfma_f32_32x32x2_f32 v[48:63], v114, v186, v[48:63]
	v_mfma_f32_32x32x2_f32 v[64:79], v114, v218, v[64:79]
	v_mfma_f32_32x32x2_f32 v[16:31], v83, v187, v[16:31]
	v_mfma_f32_32x32x2_f32 v[32:47], v83, v219, v[32:47]
	v_mfma_f32_32x32x2_f32 v[48:63], v115, v187, v[48:63]
	v_mfma_f32_32x32x2_f32 v[64:79], v115, v219, v[64:79]
	v_mfma_f32_32x32x2_f32 v[16:31], v84, v188, v[16:31]
	v_mfma_f32_32x32x2_f32 v[32:47], v84, v220, v[32:47]
	v_mfma_f32_32x32x2_f32 v[48:63], v116, v188, v[48:63]
	v_mfma_f32_32x32x2_f32 v[64:79], v116, v220, v[64:79]
	v_mfma_f32_32x32x2_f32 v[16:31], v85, v189, v[16:31]
	v_mfma_f32_32x32x2_f32 v[32:47], v85, v221, v[32:47]
	v_mfma_f32_32x32x2_f32 v[48:63], v117, v189, v[48:63]
	v_mfma_f32_32x32x2_f32 v[64:79], v117, v221, v[64:79]
	v_mfma_f32_32x32x2_f32 v[16:31], v86, v190, v[16:31]
	v_mfma_f32_32x32x2_f32 v[32:47], v86, v222, v[32:47]
	v_mfma_f32_32x32x2_f32 v[48:63], v118, v190, v[48:63]
	v_mfma_f32_32x32x2_f32 v[64:79], v118, v222, v[64:79]
	v_mfma_f32_32x32x2_f32 v[16:31], v87, v191, v[16:31]
	v_mfma_f32_32x32x2_f32 v[32:47], v87, v223, v[32:47]
	v_mfma_f32_32x32x2_f32 v[48:63], v119, v191, v[48:63]
	v_mfma_f32_32x32x2_f32 v[64:79], v119, v223, v[64:79]
	v_mfma_f32_32x32x2_f32 v[16:31], v88, v192, v[16:31]
	v_mfma_f32_32x32x2_f32 v[32:47], v88, v224, v[32:47]
	v_mfma_f32_32x32x2_f32 v[48:63], v120, v192, v[48:63]
	v_mfma_f32_32x32x2_f32 v[64:79], v120, v224, v[64:79]
	v_mfma_f32_32x32x2_f32 v[16:31], v89, v193, v[16:31]
	v_mfma_f32_32x32x2_f32 v[32:47], v89, v225, v[32:47]
	v_mfma_f32_32x32x2_f32 v[48:63], v121, v193, v[48:63]
	v_mfma_f32_32x32x2_f32 v[64:79], v121, v225, v[64:79]
	v_mfma_f32_32x32x2_f32 v[16:31], v90, v194, v[16:31]
	v_mfma_f32_32x32x2_f32 v[32:47], v90, v226, v[32:47]
	v_mfma_f32_32x32x2_f32 v[48:63], v122, v194, v[48:63]
	v_mfma_f32_32x32x2_f32 v[64:79], v122, v226, v[64:79]
	v_mfma_f32_32x32x2_f32 v[16:31], v91, v195, v[16:31]
	v_mfma_f32_32x32x2_f32 v[32:47], v91, v227, v[32:47]
	v_mfma_f32_32x32x2_f32 v[48:63], v123, v195, v[48:63]
	v_mfma_f32_32x32x2_f32 v[64:79], v123, v227, v[64:79]
	v_mfma_f32_32x32x2_f32 v[16:31], v92, v196, v[16:31]
	v_mfma_f32_32x32x2_f32 v[32:47], v92, v228, v[32:47]
	v_mfma_f32_32x32x2_f32 v[48:63], v124, v196, v[48:63]
	v_mfma_f32_32x32x2_f32 v[64:79], v124, v228, v[64:79]
	v_mfma_f32_32x32x2_f32 v[16:31], v93, v197, v[16:31]
	v_mfma_f32_32x32x2_f32 v[32:47], v93, v229, v[32:47]
	v_mfma_f32_32x32x2_f32 v[48:63], v125, v197, v[48:63]
	v_mfma_f32_32x32x2_f32 v[64:79], v125, v229, v[64:79]
	v_mfma_f32_32x32x2_f32 v[16:31], v94, v198, v[16:31]
	v_mfma_f32_32x32x2_f32 v[32:47], v94, v230, v[32:47]
	v_mfma_f32_32x32x2_f32 v[48:63], v126, v198, v[48:63]
	v_mfma_f32_32x32x2_f32 v[64:79], v126, v230, v[64:79]
	v_mfma_f32_32x32x2_f32 v[16:31], v95, v199, v[16:31]
	v_mfma_f32_32x32x2_f32 v[32:47], v95, v231, v[32:47]
	v_mfma_f32_32x32x2_f32 v[48:63], v127, v199, v[48:63]
	v_mfma_f32_32x32x2_f32 v[64:79], v127, v231, v[64:79]
	v_mfma_f32_32x32x2_f32 v[16:31], v96, v200, v[16:31]
	v_mfma_f32_32x32x2_f32 v[32:47], v96, v232, v[32:47]
	v_mfma_f32_32x32x2_f32 v[48:63], v128, v200, v[48:63]
	v_mfma_f32_32x32x2_f32 v[64:79], v128, v232, v[64:79]
	v_mfma_f32_32x32x2_f32 v[16:31], v97, v201, v[16:31]
	v_mfma_f32_32x32x2_f32 v[32:47], v97, v233, v[32:47]
	v_mfma_f32_32x32x2_f32 v[48:63], v129, v201, v[48:63]
	v_mfma_f32_32x32x2_f32 v[64:79], v129, v233, v[64:79]
	v_mfma_f32_32x32x2_f32 v[16:31], v98, v202, v[16:31]
	v_mfma_f32_32x32x2_f32 v[32:47], v98, v234, v[32:47]
; #define LAS __attribute__((address_space(3)))
; __device__ __forceinline__ void rw_post(Frame& F) {
;     ...
;                     for (int q = 0; q < 4; ++q) { f32x4 a = (f32x4){0.f, 0.f, 0.f, 0.f};
; #pragma unroll
;                         for (int i = 0; i < 16; ++i) a = __builtin_elementwise_fma(Sr[i], *(const LAS f32x4*)(cs + q * 64 + 4 * i), a);
;                         y[4 * hf + q] += (a[0] + a[1]) + (a[2] + a[3]); }
	v_mfma_f32_32x32x2_f32 v[48:63], v130, v202, v[48:63]
	v_mfma_f32_32x32x2_f32 v[64:79], v130, v234, v[64:79]
	v_mfma_f32_32x32x2_f32 v[16:31], v99, v203, v[16:31]
	v_mfma_f32_32x32x2_f32 v[32:47], v99, v235, v[32:47]
	v_mfma_f32_32x32x2_f32 v[48:63], v131, v203, v[48:63]
	v_mfma_f32_32x32x2_f32 v[64:79], v131, v235, v[64:79]
	v_mfma_f32_32x32x2_f32 v[16:31], v100, v204, v[16:31]
	v_mfma_f32_32x32x2_f32 v[32:47], v100, v244, v[32:47]
	v_mfma_f32_32x32x2_f32 v[48:63], v132, v204, v[48:63]
	v_mfma_f32_32x32x2_f32 v[64:79], v132, v244, v[64:79]
	v_mfma_f32_32x32x2_f32 v[16:31], v101, v205, v[16:31]
	v_mfma_f32_32x32x2_f32 v[32:47], v101, v245, v[32:47]
	v_mfma_f32_32x32x2_f32 v[48:63], v133, v205, v[48:63]
	v_mfma_f32_32x32x2_f32 v[64:79], v133, v245, v[64:79]
	v_mfma_f32_32x32x2_f32 v[16:31], v102, v206, v[16:31]
	v_mfma_f32_32x32x2_f32 v[32:47], v102, v246, v[32:47]
	v_mfma_f32_32x32x2_f32 v[48:63], v134, v206, v[48:63]
	v_mfma_f32_32x32x2_f32 v[64:79], v134, v246, v[64:79]
	v_mfma_f32_32x32x2_f32 v[16:31], v103, v207, v[16:31]
	v_mfma_f32_32x32x2_f32 v[32:47], v103, v247, v[32:47]
	v_mfma_f32_32x32x2_f32 v[48:63], v135, v207, v[48:63]
	v_mfma_f32_32x32x2_f32 v[64:79], v135, v247, v[64:79]
	v_mfma_f32_32x32x2_f32 v[16:31], v104, v208, v[16:31]
	v_mfma_f32_32x32x2_f32 v[32:47], v104, v248, v[32:47]
	v_mfma_f32_32x32x2_f32 v[48:63], v136, v208, v[48:63]
	v_mfma_f32_32x32x2_f32 v[64:79], v136, v248, v[64:79]
	v_mfma_f32_32x32x2_f32 v[16:31], v105, v209, v[16:31]
	v_mfma_f32_32x32x2_f32 v[32:47], v105, v249, v[32:47]
	v_mfma_f32_32x32x2_f32 v[48:63], v137, v209, v[48:63]
	v_mfma_f32_32x32x2_f32 v[64:79], v137, v249, v[64:79]
	v_mfma_f32_32x32x2_f32 v[16:31], v106, v210, v[16:31]
	v_mfma_f32_32x32x2_f32 v[32:47], v106, v250, v[32:47]
	v_mfma_f32_32x32x2_f32 v[48:63], v138, v210, v[48:63]
	v_mfma_f32_32x32x2_f32 v[64:79], v138, v250, v[64:79]
	v_mfma_f32_32x32x2_f32 v[16:31], v107, v211, v[16:31]
	v_mfma_f32_32x32x2_f32 v[32:47], v107, v251, v[32:47]
	v_mfma_f32_32x32x2_f32 v[48:63], v139, v211, v[48:63]
	v_mfma_f32_32x32x2_f32 v[64:79], v139, v251, v[64:79]
	v_mfma_f32_32x32x2_f32 v[16:31], v108, v212, v[16:31]
	v_mfma_f32_32x32x2_f32 v[32:47], v108, v252, v[32:47]
	v_mfma_f32_32x32x2_f32 v[48:63], v140, v212, v[48:63]
	v_mfma_f32_32x32x2_f32 v[64:79], v140, v252, v[64:79]
	v_mfma_f32_32x32x2_f32 v[16:31], v109, v213, v[16:31]
	v_mfma_f32_32x32x2_f32 v[32:47], v109, v253, v[32:47]
	v_mfma_f32_32x32x2_f32 v[48:63], v141, v213, v[48:63]
	v_mfma_f32_32x32x2_f32 v[64:79], v141, v253, v[64:79]
	v_mfma_f32_32x32x2_f32 v[16:31], v110, v214, v[16:31]
	v_mfma_f32_32x32x2_f32 v[32:47], v110, v254, v[32:47]
	v_mfma_f32_32x32x2_f32 v[48:63], v142, v214, v[48:63]
	v_mfma_f32_32x32x2_f32 v[64:79], v142, v254, v[64:79]
	v_mfma_f32_32x32x2_f32 v[16:31], v111, v215, v[16:31]
	v_mfma_f32_32x32x2_f32 v[32:47], v111, v255, v[32:47]
	v_mfma_f32_32x32x2_f32 v[48:63], v143, v215, v[48:63]
	v_mfma_f32_32x32x2_f32 v[64:79], v143, v255, v[64:79]
	s_nop 15
	s_nop 15
	s_nop 15
	v_permlane32_swap_b32 v16, v32
	v_permlane32_swap_b32 v17, v33
	v_permlane32_swap_b32 v18, v34
	v_permlane32_swap_b32 v19, v35
	v_permlane32_swap_b32 v20, v36
	v_permlane32_swap_b32 v21, v37
	v_permlane32_swap_b32 v22, v38
	v_permlane32_swap_b32 v23, v39
	v_permlane32_swap_b32 v24, v40
	v_permlane32_swap_b32 v25, v41
	v_permlane32_swap_b32 v26, v42
	v_permlane32_swap_b32 v27, v43
	v_permlane32_swap_b32 v28, v44
	v_permlane32_swap_b32 v29, v45
	v_permlane32_swap_b32 v30, v46
	v_permlane32_swap_b32 v31, v47
	v_permlane32_swap_b32 v48, v64
	v_permlane32_swap_b32 v49, v65
	v_permlane32_swap_b32 v50, v66
	v_permlane32_swap_b32 v51, v67
	v_permlane32_swap_b32 v52, v68
	v_permlane32_swap_b32 v53, v69
	v_permlane32_swap_b32 v54, v70
	v_permlane32_swap_b32 v55, v71
	v_permlane32_swap_b32 v56, v72
	v_permlane32_swap_b32 v57, v73
	v_permlane32_swap_b32 v58, v74
	v_permlane32_swap_b32 v59, v75
	v_permlane32_swap_b32 v60, v76
	v_permlane32_swap_b32 v61, v77
	v_permlane32_swap_b32 v62, v78
	v_permlane32_swap_b32 v63, v79
	s_branch .Lpo_s1done
